# second half-iteration QK^T/finishSM of the dense attention loop hand-interleaved (VALU spread between MFMAs, K fragment reads 6-9 deep)
# speedup vs baseline: 1.0184x; 1.0074x over previous
; #define SBAR() __builtin_amdgcn_sched_barrier(0)
; #define SLOAD(i, k0) do { const long to_ = (long)(k0) * ldk * 2; const char* vt_ = (const char*)Vh + to_; const char* kt_ = (const char*)Kh + to_; \
;     sr_[i].vs0 = *(const bf16x8*)(vt_ + toff); sr_[i].vs1 = *(const bf16x8*)(vt_ + h32 + toff); \
;     sr_[i].ks0 = *(const bf16x8*)(kt_ + toff); sr_[i].ks1 = *(const bf16x8*)(kt_ + h32 + toff); } while (0)
; #define SWAIT() do { if constexpr (SDEPTH == 2) asm volatile("s_waitcnt vmcnt(4)" ::: "memory"); else asm volatile("s_waitcnt vmcnt(0)" ::: "memory"); } while (0)
; #define RESC(a) do { if (__any((a) < 1.f)) { if (hi == 0) al_l[r32] = (a); asm volatile("s_waitcnt lgkmcnt(0)" ::: "memory"); \
;     for (int d = 0; d < 4; ++d) for (int r = 0; r < 16; ++r) o[d][r] *= al_l[crow(r, hi)]; } } while (0)
; __device__ __forceinline__ void finishSM(f32x16& p0, f32x16& p1, float alpha, float& l_reg, bf16x8& pa0, bf16x8& pa1, bf16x8& pa2, bf16x8& pa3) {
;   for (int r = 0; r < 16; ++r) p1[r] = __builtin_amdgcn_exp2f(p1[r]);
;   float ps = 0; for (int r = 0; r < 16; ++r) ps += p0[r]; for (int r = 0; r < 16; ++r) ps += p1[r];
;   { auto rr = __builtin_amdgcn_permlane32_swap(__float_as_uint(ps), __float_as_uint(ps), false, false);
;     ps = __uint_as_float(rr[0]) + __uint_as_float(rr[1]); }
;   l_reg = l_reg * alpha + ps;
;     ...
;   PK4(p0, 0, pa0); PK4(p0, 8, pa1); PK4(p1, 0, pa2); PK4(p1, 8, pa3);
;     ...
; }
; __device__ __forceinline__ void qkt(f32x16& p0, f32x16& p1, const bf16* Ks, const bf16x8* qr, int r32, int hi) {
;   p0 = f32x16{}; p1 = f32x16{};
;   for (int d0 = 0; d0 < 8; ++d0) { int cb = (d0 * 16 + hi * 8) * 2;
;     bf16x8 b0 = *reinterpret_cast<const bf16x8*>((const char*)Ks + KSWZ(r32, cb));
;     bf16x8 b1 = *reinterpret_cast<const bf16x8*>((const char*)Ks + KSWZ(32 + r32, cb));
;     p0 = __builtin_amdgcn_mfma_f32_32x32x16_bf16(b0, qr[d0], p0, 0, 0, 0);
;     p1 = __builtin_amdgcn_mfma_f32_32x32x16_bf16(b1, qr[d0], p1, 0, 0, 0); }
; }
; template <int MODE, int QMODE> ...
;     ...
;     __syncthreads(); SWAIT(); SWRITE(0, SE);
;     RESC(alB); __syncthreads();
;     SBAR(); qkt(pA0, pA1, K_lds, qr, r32, hi);
;     finishSM(pB0, pB1, alB, l_reg, pa0, pa1, pa2, pa3); SBAR();
;     if (SDEPTH == 1 || j + 3 < NT) SLOAD(SE, (j + 1 + SDEPTH) * KVBLK); SBAR();
.LBB0_175:
	s_waitcnt lgkmcnt(0)
	s_barrier
	ds_write_b128 v221, v[166:169]
	ds_write_b128 v222, v[170:173]
	ds_read_b128 v[66:69], v218 offset:32768
	ds_read_b128 v[70:73], v218 offset:40960
	ds_read_b128 v[194:197], v223 offset:32768
	ds_read_b128 v[198:201], v223 offset:40960
	ds_read_b128 v[162:165], v227 offset:32768
	ds_read_b128 v[166:169], v227 offset:40960
	ds_read_b128 v[170:173], v228 offset:32768
	ds_read_b128 v[174:177], v228 offset:40960
	v_exp_f32_e32 v82, v82
	v_exp_f32_e32 v83, v83
	s_waitcnt lgkmcnt(7)
	v_mfma_f32_32x32x16_bf16 v[114:129], v[66:69], v[134:137], 0
	v_exp_f32_e32 v84, v84
	v_exp_f32_e32 v85, v85
	v_exp_f32_e32 v86, v86
	v_exp_f32_e32 v87, v87
	v_exp_f32_e32 v88, v88
	v_exp_f32_e32 v89, v89
	v_exp_f32_e32 v90, v90
	s_waitcnt lgkmcnt(6)
	v_mfma_f32_32x32x16_bf16 v[66:81], v[70:73], v[134:137], 0
	v_exp_f32_e32 v91, v91
	v_exp_f32_e32 v92, v92
	v_exp_f32_e32 v93, v93
	v_exp_f32_e32 v94, v94
	v_exp_f32_e32 v95, v95
	v_exp_f32_e32 v96, v96
	v_exp_f32_e32 v97, v97
	ds_read_b128 v[242:245], v229 offset:32768
	ds_read_b128 v[246:249], v229 offset:40960
	ds_read_b128 v[250:253], v231 offset:32768
	s_waitcnt lgkmcnt(8)
	v_mfma_f32_32x32x16_bf16 v[114:129], v[194:197], v[142:145], v[114:129]
	v_add_f32_e32 v241, 0, v98
	v_add_f32_e32 v241, v99, v241
	v_add_f32_e32 v241, v100, v241
	v_add_f32_e32 v241, v101, v241
	v_add_f32_e32 v241, v102, v241
	v_add_f32_e32 v241, v103, v241
	s_waitcnt lgkmcnt(7)
	v_mfma_f32_32x32x16_bf16 v[66:81], v[198:201], v[142:145], v[66:81]
	v_add_f32_e32 v241, v104, v241
	v_add_f32_e32 v241, v105, v241
	v_add_f32_e32 v241, v106, v241
	v_add_f32_e32 v241, v107, v241
	v_add_f32_e32 v241, v108, v241
	v_add_f32_e32 v241, v109, v241
	s_waitcnt lgkmcnt(6)
	v_mfma_f32_32x32x16_bf16 v[114:129], v[162:165], v[130:133], v[114:129]
	v_add_f32_e32 v241, v110, v241
	v_add_f32_e32 v241, v111, v241
	v_add_f32_e32 v241, v112, v241
	v_add_f32_e32 v241, v113, v241
	v_cvt_pk_bf16_f32 v206, v98, v99
	v_cvt_pk_bf16_f32 v207, v100, v101
	s_waitcnt lgkmcnt(5)
	v_mfma_f32_32x32x16_bf16 v[66:81], v[166:169], v[130:133], v[66:81]
	ds_read_b128 v[162:165], v231 offset:40960
	ds_read_b128 v[166:169], v230 offset:32768
	v_cvt_pk_bf16_f32 v208, v102, v103
	v_cvt_pk_bf16_f32 v209, v104, v105
	v_add_f32_e32 v241, v82, v241
	v_add_f32_e32 v241, v83, v241
	v_add_f32_e32 v241, v84, v241
	s_waitcnt lgkmcnt(6)
	v_mfma_f32_32x32x16_bf16 v[114:129], v[170:173], v[138:141], v[114:129]
	v_permlane32_swap_b32_e32 v206, v208
	v_add_f32_e32 v241, v85, v241
	v_add_f32_e32 v241, v86, v241
	v_add_f32_e32 v241, v87, v241
	v_add_f32_e32 v241, v88, v241
	s_waitcnt lgkmcnt(5)
	v_mfma_f32_32x32x16_bf16 v[66:81], v[174:177], v[138:141], v[66:81]
	ds_read_b128 v[170:173], v230 offset:40960
	ds_read_b128 v[174:177], v232 offset:32768
	v_permlane32_swap_b32_e32 v207, v209
	v_add_f32_e32 v241, v89, v241
	v_add_f32_e32 v241, v90, v241
	v_add_f32_e32 v241, v91, v241
	v_add_f32_e32 v241, v92, v241
	s_waitcnt lgkmcnt(6)
	v_mfma_f32_32x32x16_bf16 v[114:129], v[242:245], v[150:153], v[114:129]
	v_cvt_pk_bf16_f32 v198, v106, v107
	v_cvt_pk_bf16_f32 v199, v108, v109
	v_cvt_pk_bf16_f32 v200, v110, v111
	v_cvt_pk_bf16_f32 v201, v112, v113
	v_add_f32_e32 v241, v93, v241
	v_add_f32_e32 v241, v94, v241
	s_waitcnt lgkmcnt(5)
	v_mfma_f32_32x32x16_bf16 v[66:81], v[246:249], v[150:153], v[66:81]
	ds_read_b128 v[242:245], v232 offset:40960
	v_permlane32_swap_b32_e32 v198, v200
	v_permlane32_swap_b32_e32 v199, v201
	v_add_f32_e32 v241, v95, v241
	v_add_f32_e32 v241, v96, v241
	s_waitcnt lgkmcnt(5)
	v_mfma_f32_32x32x16_bf16 v[114:129], v[250:253], v[158:161], v[114:129]
	v_add_f32_e32 v239, v97, v241
	v_mov_b32_e32 v240, v239
	v_cvt_pk_bf16_f32 v202, v82, v83
	v_cvt_pk_bf16_f32 v203, v84, v85
	v_cvt_pk_bf16_f32 v204, v86, v87
	v_cvt_pk_bf16_f32 v205, v88, v89
	s_waitcnt lgkmcnt(4)
	v_mfma_f32_32x32x16_bf16 v[66:81], v[162:165], v[158:161], v[66:81]
	v_permlane32_swap_b32_e32 v239, v240
	v_permlane32_swap_b32_e32 v202, v204
	v_permlane32_swap_b32_e32 v203, v205
	s_waitcnt lgkmcnt(3)
	v_mfma_f32_32x32x16_bf16 v[114:129], v[166:169], v[146:149], v[114:129]
	v_cvt_pk_bf16_f32 v194, v90, v91
	v_cvt_pk_bf16_f32 v195, v92, v93
	v_cvt_pk_bf16_f32 v196, v94, v95
	v_cvt_pk_bf16_f32 v197, v96, v97
	s_waitcnt lgkmcnt(2)
	v_mfma_f32_32x32x16_bf16 v[66:81], v[170:173], v[146:149], v[66:81]
	v_permlane32_swap_b32_e32 v194, v196
	v_permlane32_swap_b32_e32 v195, v197
	s_waitcnt lgkmcnt(1)
	v_mfma_f32_32x32x16_bf16 v[114:129], v[174:177], v[154:157], v[114:129]
	s_waitcnt lgkmcnt(0)
	v_mfma_f32_32x32x16_bf16 v[66:81], v[242:245], v[154:157], v[66:81]
	s_add_i32 s96, s96, 2
	s_cmp_ge_u32 s96, s94
	s_cselect_b64 s[16:17], -1, 0
	s_and_b64 vcc, exec, s[16:17]
	s_cbranch_vccnz .LBB0_177
	v_add_co_u32_e32 v82, vcc, 0xfffd0000, v212
	s_nop 1
	v_addc_co_u32_e32 v83, vcc, -1, v213, vcc
	global_load_dwordx4 v[166:169], v[82:83], off
	global_load_dwordx4 v[174:177], v[82:83], off offset:-512
	global_load_dwordx4 v[170:173], v[212:213], off
	global_load_dwordx4 v[162:165], v[212:213], off offset:-512
